# grid barrier: non-leader workgroups issue their L1 invalidate at arrival (before spinning, no loads in between) instead of after release
# baseline (speedup 1.0000x reference)
; __device__ __forceinline__ unsigned xb_ld(unsigned* p)              { return __hip_atomic_load(p, __ATOMIC_RELAXED, __HIP_MEMORY_SCOPE_AGENT); }
; __device__ __forceinline__ unsigned xb_add(unsigned* p, unsigned v) { return __hip_atomic_fetch_add(p, v, __ATOMIC_RELAXED, __HIP_MEMORY_SCOPE_AGENT); }
; #define XB_SPIN(cond, bar) do { unsigned _sp = 0; while (cond) { __builtin_amdgcn_s_sleep(1); \
;     if ((++_sp & 255u) == 0u) { if (xb_ld(&(bar)[XB_TMO])) break; if (_sp > XB_SPIN_CAP) { atomicAdd(&(bar)[XB_TMO], 1u); break; } } } } while (0)
; __device__ __forceinline__ void xcd_barrier(const XcdBarrier& b) {
;     ...
;         const unsigned old = xb_add(&bar[XB_XSUB(b.x)], 1u);
;         const unsigned gen = old / nloc;
;         if (old + 1u == (gen + 1u) * nloc) {
;             __builtin_amdgcn_fence(__ATOMIC_RELEASE, "agent");
;             asm volatile("s_waitcnt vmcnt(0)" ::: "memory");
;             const unsigned og = xb_add(&bar[XB_TOP], 1u);
;             const unsigned tg = og / nx;
;             if (og + 1u == (tg + 1u) * nx) xb_add(&bar[XB_TOPGEN], 1u);
;             else XB_SPIN(xb_ld(&bar[XB_TOPGEN]) == tg, bar);
;             __builtin_amdgcn_fence(__ATOMIC_ACQUIRE, "agent");
;             xb_add(&bar[XB_XGEN(b.x)], 1u);
;             asm volatile("s_waitcnt vmcnt(0)" ::: "memory");
;         } else {
;             XB_SPIN(xb_ld(&bar[XB_XGEN(b.x)]) == gen, bar);
.LBB0_101:
	s_or_b64 exec, exec, s[12:13]
	v_cvt_f32_u32_e32 v4, v2
	s_waitcnt vmcnt(0)
	v_readfirstlane_b32 s6, v3
	v_sub_u32_e32 v3, 0, v2
	v_rcp_iflag_f32_e32 v4, v4
	v_add_u32_e32 v5, s6, v1
	v_mul_f32_e32 v4, 0x4f7ffffe, v4
	v_cvt_u32_f32_e32 v4, v4
	v_mul_lo_u32 v1, v3, v4
	v_mul_hi_u32 v1, v4, v1
	v_add_u32_e32 v1, v4, v1
	v_mul_hi_u32 v1, v5, v1
	v_mul_lo_u32 v3, v1, v2
	v_sub_u32_e32 v3, v5, v3
	v_add_u32_e32 v4, 1, v1
	v_cmp_ge_u32_e32 vcc, v3, v2
	s_nop 1
	v_cndmask_b32_e32 v1, v1, v4, vcc
	v_sub_u32_e32 v4, v3, v2
	v_cndmask_b32_e32 v3, v3, v4, vcc
	v_add_u32_e32 v4, 1, v1
	v_cmp_ge_u32_e32 vcc, v3, v2
	v_add_u32_e32 v3, 1, v5
	s_nop 0
	v_cndmask_b32_e32 v1, v1, v4, vcc
	v_mul_lo_u32 v4, v2, v1
	v_add_u32_e32 v2, v4, v2
	v_cmp_ne_u32_e32 vcc, v3, v2
	s_and_saveexec_b64 s[6:7], vcc
	s_xor_b64 s[10:11], exec, s[6:7]
	s_cbranch_execz .LBB0_115
	buffer_inv sc1
	s_waitcnt lgkmcnt(0)
	v_mov_b32_e32 v0, 0x2000
	global_load_dword v0, v0, s[8:9] offset:1024 sc1
	s_add_u32 s14, s8, 0x2400
	s_addc_u32 s15, s9, 0
	s_waitcnt vmcnt(0)
	v_cmp_eq_u32_e32 vcc, v0, v1
	s_and_saveexec_b64 s[12:13], vcc
	s_cbranch_execz .LBB0_114
	s_mov_b32 s6, 1
	s_mov_b64 s[16:17], 0
	v_mov_b32_e32 v0, 0
	s_branch .LBB0_105

; __device__ __forceinline__ unsigned xb_ld(unsigned* p)              { return __hip_atomic_load(p, __ATOMIC_RELAXED, __HIP_MEMORY_SCOPE_AGENT); }
; #define XB_SPIN(cond, bar) do { unsigned _sp = 0; while (cond) { __builtin_amdgcn_s_sleep(1); \
;     if ((++_sp & 255u) == 0u) { if (xb_ld(&(bar)[XB_TMO])) break; if (_sp > XB_SPIN_CAP) { atomicAdd(&(bar)[XB_TMO], 1u); break; } } } } while (0)
; __device__ __forceinline__ void xcd_barrier(const XcdBarrier& b) {
;     ...
;         } else {
;             XB_SPIN(xb_ld(&bar[XB_XGEN(b.x)]) == gen, bar);
;             __builtin_amdgcn_fence(__ATOMIC_ACQUIRE, "agent");
;             asm volatile("s_waitcnt vmcnt(0)" ::: "memory");
.LBB0_114:
	s_or_b64 exec, exec, s[12:13]
	s_waitcnt vmcnt(0)
	s_waitcnt vmcnt(0)

; __device__ __forceinline__ unsigned xb_ld(unsigned* p)              { return __hip_atomic_load(p, __ATOMIC_RELAXED, __HIP_MEMORY_SCOPE_AGENT); }
; __device__ __forceinline__ unsigned xb_add(unsigned* p, unsigned v) { return __hip_atomic_fetch_add(p, v, __ATOMIC_RELAXED, __HIP_MEMORY_SCOPE_AGENT); }
; #define XB_SPIN(cond, bar) do { unsigned _sp = 0; while (cond) { __builtin_amdgcn_s_sleep(1); \
;     if ((++_sp & 255u) == 0u) { if (xb_ld(&(bar)[XB_TMO])) break; if (_sp > XB_SPIN_CAP) { atomicAdd(&(bar)[XB_TMO], 1u); break; } } } } while (0)
; __device__ __forceinline__ void xcd_barrier(const XcdBarrier& b) {
;     ...
;         const unsigned old = xb_add(&bar[XB_XSUB(b.x)], 1u);
;         const unsigned gen = old / nloc;
;         if (old + 1u == (gen + 1u) * nloc) {
;             __builtin_amdgcn_fence(__ATOMIC_RELEASE, "agent");
;             asm volatile("s_waitcnt vmcnt(0)" ::: "memory");
;             const unsigned og = xb_add(&bar[XB_TOP], 1u);
;             const unsigned tg = og / nx;
;             if (og + 1u == (tg + 1u) * nx) xb_add(&bar[XB_TOPGEN], 1u);
;             else XB_SPIN(xb_ld(&bar[XB_TOPGEN]) == tg, bar);
;             __builtin_amdgcn_fence(__ATOMIC_ACQUIRE, "agent");
;             xb_add(&bar[XB_XGEN(b.x)], 1u);
;             asm volatile("s_waitcnt vmcnt(0)" ::: "memory");
;         } else {
;             XB_SPIN(xb_ld(&bar[XB_XGEN(b.x)]) == gen, bar);
.LBB0_457:
	s_or_b64 exec, exec, s[10:11]
	v_cvt_f32_u32_e32 v4, v2
	s_waitcnt vmcnt(0)
	v_readfirstlane_b32 s6, v3
	v_sub_u32_e32 v3, 0, v2
	v_rcp_iflag_f32_e32 v4, v4
	v_add_u32_e32 v5, s6, v1
	v_mul_f32_e32 v4, 0x4f7ffffe, v4
	v_cvt_u32_f32_e32 v4, v4
	v_mul_lo_u32 v1, v3, v4
	v_mul_hi_u32 v1, v4, v1
	v_add_u32_e32 v1, v4, v1
	v_mul_hi_u32 v1, v5, v1
	v_mul_lo_u32 v3, v1, v2
	v_sub_u32_e32 v3, v5, v3
	v_add_u32_e32 v4, 1, v1
	v_cmp_ge_u32_e32 vcc, v3, v2
	s_nop 1
	v_cndmask_b32_e32 v1, v1, v4, vcc
	v_sub_u32_e32 v4, v3, v2
	v_cndmask_b32_e32 v3, v3, v4, vcc
	v_add_u32_e32 v4, 1, v1
	v_cmp_ge_u32_e32 vcc, v3, v2
	v_add_u32_e32 v3, 1, v5
	s_nop 0
	v_cndmask_b32_e32 v1, v1, v4, vcc
	v_mul_lo_u32 v4, v2, v1
	v_add_u32_e32 v2, v4, v2
	v_cmp_ne_u32_e32 vcc, v3, v2
	s_and_saveexec_b64 s[6:7], vcc
	s_xor_b64 s[8:9], exec, s[6:7]
	s_cbranch_execz .LBB0_471
	buffer_inv sc1
	s_waitcnt lgkmcnt(0)
	v_mov_b32_e32 v0, 0x2000
	global_load_dword v0, v0, s[4:5] offset:1024 sc1
	s_add_u32 s12, s4, 0x2400
	s_addc_u32 s13, s5, 0
	s_waitcnt vmcnt(0)
	v_cmp_eq_u32_e32 vcc, v0, v1
	s_and_saveexec_b64 s[10:11], vcc
	s_cbranch_execz .LBB0_470
	s_mov_b32 s6, 1
	s_mov_b64 s[14:15], 0
	v_mov_b32_e32 v0, 0
	s_branch .LBB0_461

; __device__ __forceinline__ unsigned xb_ld(unsigned* p)              { return __hip_atomic_load(p, __ATOMIC_RELAXED, __HIP_MEMORY_SCOPE_AGENT); }
; #define XB_SPIN(cond, bar) do { unsigned _sp = 0; while (cond) { __builtin_amdgcn_s_sleep(1); \
;     if ((++_sp & 255u) == 0u) { if (xb_ld(&(bar)[XB_TMO])) break; if (_sp > XB_SPIN_CAP) { atomicAdd(&(bar)[XB_TMO], 1u); break; } } } } while (0)
; __device__ __forceinline__ void xcd_barrier(const XcdBarrier& b) {
;     ...
;         } else {
;             XB_SPIN(xb_ld(&bar[XB_XGEN(b.x)]) == gen, bar);
;             __builtin_amdgcn_fence(__ATOMIC_ACQUIRE, "agent");
;             asm volatile("s_waitcnt vmcnt(0)" ::: "memory");
.LBB0_470:
	s_or_b64 exec, exec, s[10:11]
	s_waitcnt vmcnt(0)
	s_waitcnt vmcnt(0)

; __device__ __forceinline__ unsigned xb_ld(unsigned* p)              { return __hip_atomic_load(p, __ATOMIC_RELAXED, __HIP_MEMORY_SCOPE_AGENT); }
; __device__ __forceinline__ unsigned xb_add(unsigned* p, unsigned v) { return __hip_atomic_fetch_add(p, v, __ATOMIC_RELAXED, __HIP_MEMORY_SCOPE_AGENT); }
; #define XB_SPIN(cond, bar) do { unsigned _sp = 0; while (cond) { __builtin_amdgcn_s_sleep(1); \
;     if ((++_sp & 255u) == 0u) { if (xb_ld(&(bar)[XB_TMO])) break; if (_sp > XB_SPIN_CAP) { atomicAdd(&(bar)[XB_TMO], 1u); break; } } } } while (0)
; __device__ __forceinline__ void xcd_barrier(const XcdBarrier& b) {
;     ...
;         const unsigned old = xb_add(&bar[XB_XSUB(b.x)], 1u);
;         const unsigned gen = old / nloc;
;         if (old + 1u == (gen + 1u) * nloc) {
;             __builtin_amdgcn_fence(__ATOMIC_RELEASE, "agent");
;             asm volatile("s_waitcnt vmcnt(0)" ::: "memory");
;             const unsigned og = xb_add(&bar[XB_TOP], 1u);
;             const unsigned tg = og / nx;
;             if (og + 1u == (tg + 1u) * nx) xb_add(&bar[XB_TOPGEN], 1u);
;             else XB_SPIN(xb_ld(&bar[XB_TOPGEN]) == tg, bar);
;             __builtin_amdgcn_fence(__ATOMIC_ACQUIRE, "agent");
;             xb_add(&bar[XB_XGEN(b.x)], 1u);
;             asm volatile("s_waitcnt vmcnt(0)" ::: "memory");
;         } else {
;             XB_SPIN(xb_ld(&bar[XB_XGEN(b.x)]) == gen, bar);
.LBB0_968:
	s_or_b64 exec, exec, s[8:9]
	v_cvt_f32_u32_e32 v4, v2
	s_waitcnt vmcnt(0)
	v_readfirstlane_b32 s6, v3
	v_sub_u32_e32 v3, 0, v2
	v_rcp_iflag_f32_e32 v4, v4
	v_add_u32_e32 v5, s6, v1
	v_mul_f32_e32 v4, 0x4f7ffffe, v4
	v_cvt_u32_f32_e32 v4, v4
	v_mul_lo_u32 v1, v3, v4
	v_mul_hi_u32 v1, v4, v1
	v_add_u32_e32 v1, v4, v1
	v_mul_hi_u32 v1, v5, v1
	v_mul_lo_u32 v3, v1, v2
	v_sub_u32_e32 v3, v5, v3
	v_add_u32_e32 v4, 1, v1
	v_cmp_ge_u32_e32 vcc, v3, v2
	s_nop 1
	v_cndmask_b32_e32 v1, v1, v4, vcc
	v_sub_u32_e32 v4, v3, v2
	v_cndmask_b32_e32 v3, v3, v4, vcc
	v_add_u32_e32 v4, 1, v1
	v_cmp_ge_u32_e32 vcc, v3, v2
	v_add_u32_e32 v3, 1, v5
	s_nop 0
	v_cndmask_b32_e32 v1, v1, v4, vcc
	v_mul_lo_u32 v4, v2, v1
	v_add_u32_e32 v2, v4, v2
	v_cmp_ne_u32_e32 vcc, v3, v2
	s_and_saveexec_b64 s[6:7], vcc
	s_xor_b64 s[6:7], exec, s[6:7]
	s_cbranch_execz .LBB0_982
	buffer_inv sc1
	s_waitcnt lgkmcnt(0)
	v_mov_b32_e32 v0, 0x2000
	global_load_dword v0, v0, s[4:5] offset:1024 sc1
	s_add_u32 s10, s4, 0x2400
	s_addc_u32 s11, s5, 0
	s_waitcnt vmcnt(0)
	v_cmp_eq_u32_e32 vcc, v0, v1
	s_and_saveexec_b64 s[8:9], vcc
	s_cbranch_execz .LBB0_981
	s_mov_b32 s19, 1
	s_mov_b64 s[12:13], 0
	v_mov_b32_e32 v0, 0
	s_branch .LBB0_972

; __device__ __forceinline__ unsigned xb_ld(unsigned* p)              { return __hip_atomic_load(p, __ATOMIC_RELAXED, __HIP_MEMORY_SCOPE_AGENT); }
; #define XB_SPIN(cond, bar) do { unsigned _sp = 0; while (cond) { __builtin_amdgcn_s_sleep(1); \
;     if ((++_sp & 255u) == 0u) { if (xb_ld(&(bar)[XB_TMO])) break; if (_sp > XB_SPIN_CAP) { atomicAdd(&(bar)[XB_TMO], 1u); break; } } } } while (0)
; __device__ __forceinline__ void xcd_barrier(const XcdBarrier& b) {
;     ...
;         } else {
;             XB_SPIN(xb_ld(&bar[XB_XGEN(b.x)]) == gen, bar);
;             __builtin_amdgcn_fence(__ATOMIC_ACQUIRE, "agent");
;             asm volatile("s_waitcnt vmcnt(0)" ::: "memory");
.LBB0_981:
	s_or_b64 exec, exec, s[8:9]
	s_waitcnt vmcnt(0)
	s_waitcnt vmcnt(0)
